# in-proj L1: odd CUs start 2 sleeps late (deliberate stagger, no slack)
# baseline (speedup 1.0000x reference)
; __global__ void __launch_bounds__(512, 2) mega(P p) {
;     ...
;       const int l = (ph - 2) >> 2, s = (ph - 2) & 3;
;       if (s == 0) { for (int rr = 0; rr < REP_INPROJ; ++rr) { if (rr) cg::this_grid().sync(); phase_inproj(p, l, lds); } }
.LBB0_74:
	s_andn2_b64 vcc, exec, s[0:1]
	s_cbranch_vccnz .LBB0_941
	s_cmp_lg_u32 s24, 1
	s_mov_b64 s[0:1], -1
	s_cbranch_scc0 .LBB0_812
	v_readlane_b32 s0, v254, 9
	v_readlane_b32 s1, v254, 10
	v_mov_b32_e32 v0, v195
	s_andn2_b64 vcc, exec, s[0:1]
	s_cbranch_vccnz .LBB0_811
	s_cmp_lg_u32 s50, 1
	s_cbranch_scc1 .Ldephase_l1_skip
	s_bitcmp1_b32 s84, 0
	s_cbranch_scc0 .Ldephase_in_done
	s_sleep 127
	s_sleep 127
	s_branch .Ldephase_in_done
